# attention item order rotated for workgroups < 256 (dilated/memory items first, MLA last) so the two workgroups of a CU run different item types side by side
# speedup vs baseline: 1.0011x; 1.0011x over previous
; DI int BID() { int b = (int)__builtin_amdgcn_workgroup_id_x(); asm volatile("" : "+s"(b)); return b; }
; DI void item_attn(const Params& p, int l, const Chunk& ck, int it, char* smem) {
;   const int S = ck.S;
;   if (it < 8 * MTN) {
;     static_assert(8 * MTN == 1024, "MLA item swizzle assumes 1024 items");
;     const int rnd = it >> 9, x = it & 7, jj = (it & 511) >> 3; const int qs = ck.sshift - 7, ppx = 64 >> qs;
;     const int bh = rnd * (8 * ppx) + x * ppx + (jj >> qs), qblk = jj & ((1 << qs) - 1);
;     const int h = bh & 7, bl = bh >> 3; const int t0 = qblk * 128, lt0 = bl * S + t0;
;     const u16* Q = (const u16*)(p.ws + OFF_QM) + (size_t)lt0 * 768 + h * 96;
;     const u16* K = (const u16*)(p.ws + OFF_KM) + (size_t)(bl * S) * 768 + h * 96;
;     const u16* Vt = (const u16*)(p.ws + OFF_VMT) + ((size_t)(bl * 8 + h) * 64) * S;
;     u16* O = (u16*)(p.ws + OFF_BR) + (size_t)(1 * CT + lt0) * 512 + h * 64;
;     (void)t0;
;     attn_block<96, 64, false>(Q, 768, K, 768, Vt, S, S, t0, 0.f, O, 512, nullptr, 0, smem);
; DI void run_phase(const Params& p, int ph, int l, int c, char* smem) {
;     ...
;     case PH_ATTN: for (int t = BID(); t < 24 * MTN; t += gridDim.x) item_attn(p, l, ck, t, smem); break;
.LBB1_274:
	s_andn2_b64 vcc, exec, s[26:27]
	s_cbranch_vccnz .LBB1_428
	v_readlane_b32 s0, v255, 30
	s_cmp_lt_i32 s0, 3
	s_mov_b64 s[20:21], -1
	s_cbranch_scc1 .LBB1_378
	v_readlane_b32 s0, v255, 30
	s_cmp_gt_i32 s0, 3
	s_cbranch_scc0 .LBB1_336
	s_mov_b32 s16, s92
	s_cmpk_gt_i32 s16, 0xbff
	s_cbranch_scc1 .LBB1_335
	v_readlane_b32 s20, v255, 28
	s_add_i32 s35, s44, -7
	s_mul_hi_i32 s0, s20, 0x600000
	s_mul_i32 s17, s20, 0x600000
	s_lshl_b32 s20, -1, s35
	s_add_i32 s47, s2, 0x3fff
	s_lshl_b32 s48, s2, 7
	s_lshr_b32 s42, 64, s35
	s_not_b32 s43, s20
	s_lshl_b32 s74, s2, 6
	s_lshr_b32 s75, s2, 6
	s_add_u32 s49, s18, 0x11080000
	s_addc_u32 s50, s19, 0
	s_add_u32 s17, s18, s17
	s_addc_u32 s0, s19, s0
	s_add_u32 s51, s17, 0x5380000
	s_addc_u32 s20, s0, 0
	v_readlane_b32 s21, v255, 29
	v_writelane_b32 v255, s20, 31
	s_add_u32 s17, s17, 0x5f80000
	v_writelane_b32 v255, s17, 32
	s_addc_u32 s0, s0, 0
	v_writelane_b32 v255, s0, 33
	s_add_u32 s0, s18, 0x6b80000
	v_writelane_b32 v255, s0, 34
	s_addc_u32 s0, s19, 0
	v_writelane_b32 v255, s0, 35
	s_add_u32 s0, s18, 0x16080000
	v_writelane_b32 v255, s0, 36
	s_addc_u32 s0, s19, 0
	v_writelane_b32 v255, s0, 37
	s_add_u32 s0, s18, 0x19080000
	v_writelane_b32 v255, s0, 38
	s_addc_u32 s0, s19, 0
	v_writelane_b32 v255, s0, 39
	s_add_u32 s0, s18, 0xcb80000
	v_writelane_b32 v255, s0, 40
	s_addc_u32 s0, s19, 0
	v_writelane_b32 v255, s0, 41
	s_add_u32 s0, s18, 0x9b80000
	v_writelane_b32 v255, s0, 42
	s_addc_u32 s0, s19, 0
	s_add_u32 s93, s18, 0x12080000
	s_addc_u32 s94, s19, 0
	s_add_u32 s17, s18, 0x15080000
	s_addc_u32 s34, s19, 0
	s_add_u32 s79, s18, 0x13880000
	s_addc_u32 s92, s19, 0
	s_add_u32 s52, s18, 0x19140000
	v_writelane_b32 v255, s0, 43
	s_addc_u32 s53, s19, 0
	s_mul_i32 s54, s16, s42
	s_mov_b32 s55, s16
	s_mov_b32 s98, 6
	s_cmpk_lt_u32 s92, 0x100
	s_cselect_b32 s0, 0x400, 0
	s_add_i32 s55, s55, s0
	s_add_i32 s16, s16, s0
	s_mul_i32 s54, s16, s42
	s_branch .LBB1_281

; DI int BID() { int b = (int)__builtin_amdgcn_workgroup_id_x(); asm volatile("" : "+s"(b)); return b; }
; DI void run_phase(const Params& p, int ph, int l, int c, char* smem) {
;     ...
;     case PH_ATTN: for (int t = BID(); t < 24 * MTN; t += gridDim.x) item_attn(p, l, ck, t, smem); break;
.LBB1_280:
	s_mul_i32 s0, s78, s42
	s_add_i32 s55, s55, s78
	s_add_i32 s16, s16, s78
	s_add_i32 s54, s54, s0
	s_cmpk_gt_i32 s55, 0xbff
	s_cbranch_scc0 .Lattn_nowrap
	s_sub_i32 s55, s55, 0xc00
	s_sub_i32 s16, s16, 0xc00
	s_mul_i32 s54, s16, s42
.Lattn_nowrap:
	s_sub_u32 s98, s98, 1
	s_cmp_eq_u32 s98, 0
	s_cbranch_scc1 .LBB1_335
